# P1->P2 seam of layer 0: all 1280 filler weight-conversion items run on workgroups 192..255 (they finish P1 early), others go straight to the barrier wait
# speedup vs baseline: 1.0177x; 1.0050x over previous
.LBB0_427:
	s_or_b64 exec, exec, s[0:1]
	v_mov_b32_e32 v0, v252
	v_readlane_b32 s3, v254, 33
	v_readfirstlane_b32 s0, v0
	s_ashr_i32 s2, s0, 6
	s_add_i32 s26, s3, s2
	s_cmpk_lg_i32 s86, 0x100
	s_cbranch_scc1 .Lseam1_init_done
	s_sub_i32 s3, s96, 0xc0
	s_lshl_b32 s26, s3, 3
	s_add_i32 s26, s26, s2
	s_addk_i32 s26, 0x1c80
	s_cmp_lt_i32 s3, 0
	s_cselect_b32 s26, 0x2180, s26
.Lseam1_init_done:
	s_mov_b64 s[0:1], s[20:21]
	s_cmpk_gt_i32 s26, 0x217f
	s_cbranch_scc1 .LBB0_476
	s_add_u32 s27, s0, 0x200000
	s_addc_u32 s36, s1, 0
	s_add_u32 s37, s0, 0x3e00000
	s_addc_u32 s38, s1, 0
	s_add_u32 s39, s0, 0x4e00000
	s_addc_u32 s40, s1, 0
	s_add_u32 s41, s0, 0x5e00000
	s_addc_u32 s42, s1, 0
	s_add_u32 s43, s0, 0x10000
	s_addc_u32 s44, s1, 0
	v_and_b32_e32 v2, 63, v0
	v_bfe_u32 v69, v0, 4, 2
	v_bfe_u32 v80, v0, 3, 3
	v_lshlrev_b32_e32 v0, 3, v0
	s_add_u32 s45, s0, 0x14000
	s_mulk_i32 s2, 0x4100
	v_and_b32_e32 v70, 56, v0
	s_addc_u32 s46, s1, 0
	s_add_i32 s0, s2, 0
	v_lshlrev_b32_e32 v168, 2, v2
	v_mul_u32_u24_e32 v0, 0x104, v70
	v_lshlrev_b32_e32 v3, 2, v80
	v_and_b32_e32 v68, 60, v168
	v_add3_u32 v81, s0, v0, v3
	v_or_b32_e32 v0, 4, v69
	v_lshl_add_u32 v1, v68, 2, s0
	s_movk_i32 s1, 0x104
	v_mul_u32_u24_e32 v0, 0x104, v0
	v_mad_u32_u24 v71, v69, s1, v1
	v_or_b32_e32 v82, 8, v80
	v_or_b32_e32 v83, 16, v80
	v_or_b32_e32 v84, 24, v80
	v_or_b32_e32 v85, 32, v80
	v_or_b32_e32 v86, 40, v80
	v_or_b32_e32 v87, 48, v80
	v_or_b32_e32 v88, 56, v80
	v_add_u32_e32 v89, s0, v168
	v_lshl_add_u64 v[72:73], s[16:17], 0, v[168:169]
	v_lshlrev_b32_e32 v74, 2, v2
	v_add_u32_e32 v90, v1, v0
	s_branch .LBB0_430
.LBB0_429:
	v_readlane_b32 s0, v253, 34
	s_cmpk_eq_i32 s86, 0x100
	s_cselect_b32 s0, 0x200, s0
	s_add_i32 s26, s26, s0
	s_cmpk_gt_i32 s26, 0x217f
	s_cbranch_scc1 .LBB0_476
